# asymmetric P0 split 0/1/4/6 per batch (with block-id permutation)
# baseline (speedup 1.0000x reference)
.LBB0_155:
	s_or_b64 exec, exec, s[0:1]
	s_mov_b32 s100, 1
	s_lshr_b32 s0, s83, 6
	s_and_b32 s1, s83, 63
	s_movk_i32 s4, 0
	s_movk_i32 s5, 512
	s_cmp_eq_u32 s0, 1
	s_cselect_b32 s4, 1, s4
	s_cselect_b32 s5, 512, s5
	s_cmp_eq_u32 s0, 2
	s_cselect_b32 s4, 4, s4
	s_cselect_b32 s5, 576, s5
	s_cmp_eq_u32 s0, 3
	s_cselect_b32 s4, 6, s4
	s_cselect_b32 s5, 832, s5
	s_cmp_eq_u32 s4, 0
	s_cbranch_scc1 .Lp0_second_done
	s_mul_i32 s6, s1, s4
	s_add_i32 s8, s5, s6
	s_add_i32 s10, s8, s4
	s_mul_i32 s3, s62, 0x2080
	s_mov_b32 s33, s3
	s_branch .LBB0_34
